# DSA score steps: causal-compare VALU moved behind the last chain MFMA so it fills the MFMA-to-VALU wait window (s_nop shortened to keep 12 states)
# baseline (speedup 1.0000x reference)
; DI f32x16 mfma32(bf16x8 a, bf16x8 b, f32x16 c) { return __builtin_amdgcn_mfma_f32_32x32x16_bf16(a, b, c, 0, 0, 0); }
; DI u32 mono_key(float f) { u32 u = __float_as_uint(f); return (u & 0x80000000u) ? ~u : (u | 0x80000000u); }
; DI void dsa_item(const Params& p, int l, int tile32, int b, char* smem) {
;     ...
;       for (int t = 0; t < 4; ++t) {
;         const int key = (g * 4 + t) * 32 + c31;
;         f32x16 acc;
; #pragma unroll
;         for (int j = 0; j < 16; ++j) acc[j] = 0.f;
; #pragma unroll
;         for (int s = 0; s < 4; ++s) acc = mfma32(qa[s], kc[t][s], acc);
;         f32x2 ss2 = f32x2{0.f, 0.f};
; #pragma unroll
;         for (int hq = 0; hq < 8; ++hq) {
;           const f32x2 rr = f32x2{__builtin_amdgcn_fmed3f(acc[2 * hq], 0.f, 3.0e38f), __builtin_amdgcn_fmed3f(acc[2 * hq + 1], 0.f, 3.0e38f)};
;           ss2 = __builtin_elementwise_fma(wq2[hq], rr, ss2);
;         }
;         const float s0 = ss2.x, s1 = ss2.y;
;         const u32 k0 = mono_key(s0), k1 = mono_key(s1);
;         const bool c0 = (key <= qpos0) && (k0 > tauA), c1 = (key <= qpos0 + 1) && (k1 > tauB);
;         const u64 m0 = __ballot(c0), m1 = __ballot(c1);
;         if (m0 | m1) {
;           const u32 h0 = hh ? (u32)(m0 >> 32) : (u32)m0, h1 = hh ? (u32)(m1 >> 32) : (u32)m1;
;           const int pA = (hh ? cnt2 : cnt0) + __popc(h0 & lmask), pB = (hh ? cnt3 : cnt1) + __popc(h1 & lmask);
;           if (c0) { ckey[(2 * hh) * DCAP + pA] = k0; cidx[(2 * hh) * DCAP + pA] = (u16)key; }
;           if (c1) { ckey[(2 * hh + 1) * DCAP + pB] = k1; cidx[(2 * hh + 1) * DCAP + pB] = (u16)key; }
;           cnt0 += __popc((u32)m0); cnt2 += __popc((u32)(m0 >> 32));
;           cnt1 += __popc((u32)m1); cnt3 += __popc((u32)(m1 >> 32));
;         }
.LBB0_499:
	s_or_b64 exec, exec, s[2:3]
	v_mfma_f32_32x32x16_bf16 v[2:17], v[18:21], v[2:5], 0
	v_cndmask_b32_e32 v0, v223, v224, vcc
	v_mfma_f32_32x32x16_bf16 v[2:17], v[22:25], v[98:101], v[2:17]
	v_mfma_f32_32x32x16_bf16 v[2:17], v[26:29], v[94:97], v[2:17]
	v_mfma_f32_32x32x16_bf16 v[2:17], v[30:33], v[90:93], v[2:17]
	v_lshl_or_b32 v95, s54, 7, v192
	v_cndmask_b32_e32 v94, v221, v222, vcc
	v_cmp_le_i32_e64 s[0:1], v95, v217
	v_cmp_le_i32_e64 s[2:3], v95, v219
	s_nop 7
	v_med3_f32 v2, v2, 0, v204
	v_med3_f32 v3, v3, 0, v204
	v_med3_f32 v4, v4, 0, v204
	v_med3_f32 v5, v5, 0, v204
	v_fma_f32 v2, v178, v2, 0
	v_fma_f32 v3, v179, v3, 0
	v_med3_f32 v6, v6, 0, v204
	v_med3_f32 v7, v7, 0, v204
	v_fmac_f32_e32 v2, v38, v4
	v_fmac_f32_e32 v3, v39, v5
	v_med3_f32 v8, v8, 0, v204
	v_med3_f32 v9, v9, 0, v204
	v_fmac_f32_e32 v2, v180, v6
	v_fmac_f32_e32 v3, v181, v7
	v_med3_f32 v10, v10, 0, v204
	v_med3_f32 v11, v11, 0, v204
	v_fmac_f32_e32 v2, v40, v8
	v_fmac_f32_e32 v3, v41, v9
	v_med3_f32 v12, v12, 0, v204
	v_med3_f32 v13, v13, 0, v204
	v_fmac_f32_e32 v2, v182, v10
	v_fmac_f32_e32 v3, v183, v11
	v_med3_f32 v14, v14, 0, v204
	v_med3_f32 v15, v15, 0, v204
	v_fmac_f32_e32 v2, v34, v12
	v_fmac_f32_e32 v3, v35, v13
	v_med3_f32 v16, v16, 0, v204
	v_med3_f32 v17, v17, 0, v204
	v_fmac_f32_e32 v2, v184, v14
	v_fmac_f32_e32 v3, v185, v15
	v_fma_f32 v4, v36, v16, v2
	v_fma_f32 v5, v37, v17, v3
	v_ashrrev_i32_e32 v2, 31, v4
	v_ashrrev_i32_e32 v6, 31, v5
	v_or_b32_e32 v2, 0x80000000, v2
	v_or_b32_e32 v6, 0x80000000, v6
	v_xor_b32_e32 v3, v4, v2
	v_xor_b32_e32 v2, v5, v6
	v_cmp_gt_u32_e64 s[4:5], v3, v0
	v_cmp_gt_u32_e64 s[6:7], v2, v94
	s_and_b64 s[10:11], s[0:1], s[4:5]
	s_and_b64 s[4:5], s[2:3], s[6:7]
	s_or_b64 s[6:7], s[10:11], s[4:5]
	s_cbranch_scc0 .LBB0_505
	s_and_b64 s[0:1], s[10:11], exec
	s_and_b64 s[2:3], s[4:5], exec
	s_and_saveexec_b64 s[6:7], s[10:11]
	s_cbranch_execz .LBB0_502
	v_mov_b32_e32 v4, s1
	v_mov_b32_e32 v5, s0
	v_cndmask_b32_e32 v4, v4, v5, vcc
	v_and_b32_e32 v4, v4, v218
	v_bcnt_u32_b32 v4, v4, 0
	v_cndmask_b32_e32 v5, v187, v173, vcc
	v_add3_u32 v4, v5, v214, v4
	v_lshl_add_u32 v5, v4, 2, v190
	ds_write_b32 v5, v3
	v_lshlrev_b32_e32 v3, 1, v4
	v_sub_u32_e32 v3, v5, v3
	ds_write_b16 v3, v95 offset:10240

; DI f32x16 mfma32(bf16x8 a, bf16x8 b, f32x16 c) { return __builtin_amdgcn_mfma_f32_32x32x16_bf16(a, b, c, 0, 0, 0); }
; DI u32 mono_key(float f) { u32 u = __float_as_uint(f); return (u & 0x80000000u) ? ~u : (u | 0x80000000u); }
; DI void dsa_item(const Params& p, int l, int tile32, int b, char* smem) {
;     ...
;       for (int t = 0; t < 4; ++t) {
;         const int key = (g * 4 + t) * 32 + c31;
;         f32x16 acc;
; #pragma unroll
;         for (int j = 0; j < 16; ++j) acc[j] = 0.f;
; #pragma unroll
;         for (int s = 0; s < 4; ++s) acc = mfma32(qa[s], kc[t][s], acc);
;         f32x2 ss2 = f32x2{0.f, 0.f};
; #pragma unroll
;         for (int hq = 0; hq < 8; ++hq) {
;           const f32x2 rr = f32x2{__builtin_amdgcn_fmed3f(acc[2 * hq], 0.f, 3.0e38f), __builtin_amdgcn_fmed3f(acc[2 * hq + 1], 0.f, 3.0e38f)};
;           ss2 = __builtin_elementwise_fma(wq2[hq], rr, ss2);
;         }
;         const float s0 = ss2.x, s1 = ss2.y;
;         const u32 k0 = mono_key(s0), k1 = mono_key(s1);
;         const bool c0 = (key <= qpos0) && (k0 > tauA), c1 = (key <= qpos0 + 1) && (k1 > tauB);
;         const u64 m0 = __ballot(c0), m1 = __ballot(c1);
;         if (m0 | m1) {
;           const u32 h0 = hh ? (u32)(m0 >> 32) : (u32)m0, h1 = hh ? (u32)(m1 >> 32) : (u32)m1;
;           const int pA = (hh ? cnt2 : cnt0) + __popc(h0 & lmask), pB = (hh ? cnt3 : cnt1) + __popc(h1 & lmask);
;           if (c0) { ckey[(2 * hh) * DCAP + pA] = k0; cidx[(2 * hh) * DCAP + pA] = (u16)key; }
;           if (c1) { ckey[(2 * hh + 1) * DCAP + pB] = k1; cidx[(2 * hh + 1) * DCAP + pB] = (u16)key; }
;           cnt0 += __popc((u32)m0); cnt2 += __popc((u32)(m0 >> 32));
;           cnt1 += __popc((u32)m1); cnt3 += __popc((u32)(m1 >> 32));
;         }
.LBB0_505:
	v_mfma_f32_32x32x16_bf16 v[2:17], v[18:21], v[86:89], 0
	v_mfma_f32_32x32x16_bf16 v[2:17], v[22:25], v[82:85], v[2:17]
	v_mfma_f32_32x32x16_bf16 v[2:17], v[26:29], v[78:81], v[2:17]
	v_mfma_f32_32x32x16_bf16 v[2:17], v[30:33], v[74:77], v[2:17]
	v_or_b32_e32 v78, 32, v95
	v_cmp_le_i32_e64 s[0:1], v78, v217
	v_cmp_le_i32_e64 s[2:3], v78, v219
	s_nop 8
	v_med3_f32 v2, v2, 0, v204
	v_med3_f32 v3, v3, 0, v204
	v_med3_f32 v4, v4, 0, v204
	v_med3_f32 v5, v5, 0, v204
	v_fma_f32 v2, v178, v2, 0
	v_fma_f32 v3, v179, v3, 0
	v_med3_f32 v6, v6, 0, v204
	v_med3_f32 v7, v7, 0, v204
	v_fmac_f32_e32 v2, v38, v4
	v_fmac_f32_e32 v3, v39, v5
	v_med3_f32 v8, v8, 0, v204
	v_med3_f32 v9, v9, 0, v204
	v_fmac_f32_e32 v2, v180, v6
	v_fmac_f32_e32 v3, v181, v7
	v_med3_f32 v10, v10, 0, v204
	v_med3_f32 v11, v11, 0, v204
	v_fmac_f32_e32 v2, v40, v8
	v_fmac_f32_e32 v3, v41, v9
	v_med3_f32 v12, v12, 0, v204
	v_med3_f32 v13, v13, 0, v204
	v_fmac_f32_e32 v2, v182, v10
	v_fmac_f32_e32 v3, v183, v11
	v_med3_f32 v14, v14, 0, v204
	v_med3_f32 v15, v15, 0, v204
	v_fmac_f32_e32 v2, v34, v12
	v_fmac_f32_e32 v3, v35, v13
	v_med3_f32 v16, v16, 0, v204
	v_med3_f32 v17, v17, 0, v204
	v_fmac_f32_e32 v2, v184, v14
	v_fmac_f32_e32 v3, v185, v15
	v_fma_f32 v4, v36, v16, v2
	v_fma_f32 v5, v37, v17, v3
	v_ashrrev_i32_e32 v2, 31, v4
	v_ashrrev_i32_e32 v6, 31, v5
	v_or_b32_e32 v2, 0x80000000, v2
	v_or_b32_e32 v6, 0x80000000, v6
	v_xor_b32_e32 v3, v4, v2
	v_xor_b32_e32 v2, v5, v6
	v_cmp_gt_u32_e64 s[4:5], v3, v0
	v_cmp_gt_u32_e64 s[6:7], v2, v94
	s_and_b64 s[10:11], s[0:1], s[4:5]
	s_and_b64 s[4:5], s[2:3], s[6:7]
	s_or_b64 s[6:7], s[10:11], s[4:5]
	s_cbranch_scc0 .LBB0_511
	s_and_b64 s[2:3], s[10:11], exec
	s_and_b64 s[0:1], s[4:5], exec
	s_and_saveexec_b64 s[6:7], s[10:11]
	s_cbranch_execz .LBB0_508
	v_mov_b32_e32 v4, s3
	v_mov_b32_e32 v5, s2
	v_cndmask_b32_e32 v4, v4, v5, vcc
	v_and_b32_e32 v4, v4, v218
	v_bcnt_u32_b32 v4, v4, 0
	v_cndmask_b32_e32 v5, v187, v173, vcc
	v_add3_u32 v4, v5, v214, v4
	v_lshl_add_u32 v5, v4, 2, v190
	ds_write_b32 v5, v3
	v_lshlrev_b32_e32 v3, 1, v4
	v_sub_u32_e32 v3, v5, v3
	ds_write_b16 v3, v78 offset:10240

; DI f32x16 mfma32(bf16x8 a, bf16x8 b, f32x16 c) { return __builtin_amdgcn_mfma_f32_32x32x16_bf16(a, b, c, 0, 0, 0); }
; DI u32 mono_key(float f) { u32 u = __float_as_uint(f); return (u & 0x80000000u) ? ~u : (u | 0x80000000u); }
; DI void dsa_item(const Params& p, int l, int tile32, int b, char* smem) {
;     ...
;       for (int t = 0; t < 4; ++t) {
;         const int key = (g * 4 + t) * 32 + c31;
;         f32x16 acc;
; #pragma unroll
;         for (int j = 0; j < 16; ++j) acc[j] = 0.f;
; #pragma unroll
;         for (int s = 0; s < 4; ++s) acc = mfma32(qa[s], kc[t][s], acc);
;         f32x2 ss2 = f32x2{0.f, 0.f};
; #pragma unroll
;         for (int hq = 0; hq < 8; ++hq) {
;           const f32x2 rr = f32x2{__builtin_amdgcn_fmed3f(acc[2 * hq], 0.f, 3.0e38f), __builtin_amdgcn_fmed3f(acc[2 * hq + 1], 0.f, 3.0e38f)};
;           ss2 = __builtin_elementwise_fma(wq2[hq], rr, ss2);
;         }
;         const float s0 = ss2.x, s1 = ss2.y;
;         const u32 k0 = mono_key(s0), k1 = mono_key(s1);
;         const bool c0 = (key <= qpos0) && (k0 > tauA), c1 = (key <= qpos0 + 1) && (k1 > tauB);
;         const u64 m0 = __ballot(c0), m1 = __ballot(c1);
;         if (m0 | m1) {
;           const u32 h0 = hh ? (u32)(m0 >> 32) : (u32)m0, h1 = hh ? (u32)(m1 >> 32) : (u32)m1;
;           const int pA = (hh ? cnt2 : cnt0) + __popc(h0 & lmask), pB = (hh ? cnt3 : cnt1) + __popc(h1 & lmask);
;           if (c0) { ckey[(2 * hh) * DCAP + pA] = k0; cidx[(2 * hh) * DCAP + pA] = (u16)key; }
;           if (c1) { ckey[(2 * hh + 1) * DCAP + pB] = k1; cidx[(2 * hh + 1) * DCAP + pB] = (u16)key; }
;           cnt0 += __popc((u32)m0); cnt2 += __popc((u32)(m0 >> 32));
;           cnt1 += __popc((u32)m1); cnt3 += __popc((u32)(m1 >> 32));
;         }
.LBB0_511:
	v_mfma_f32_32x32x16_bf16 v[2:17], v[18:21], v[70:73], 0
	v_mfma_f32_32x32x16_bf16 v[2:17], v[22:25], v[66:69], v[2:17]
	v_mfma_f32_32x32x16_bf16 v[2:17], v[26:29], v[62:65], v[2:17]
	v_mfma_f32_32x32x16_bf16 v[2:17], v[30:33], v[58:61], v[2:17]
	v_or_b32_e32 v62, 64, v95
	v_cmp_le_i32_e64 s[0:1], v62, v217
	v_cmp_le_i32_e64 s[2:3], v62, v219
	s_nop 8
	v_med3_f32 v2, v2, 0, v204
	v_med3_f32 v3, v3, 0, v204
	v_med3_f32 v4, v4, 0, v204
	v_med3_f32 v5, v5, 0, v204
	v_fma_f32 v2, v178, v2, 0
	v_fma_f32 v3, v179, v3, 0
	v_med3_f32 v6, v6, 0, v204
	v_med3_f32 v7, v7, 0, v204
	v_fmac_f32_e32 v2, v38, v4
	v_fmac_f32_e32 v3, v39, v5
	v_med3_f32 v8, v8, 0, v204
	v_med3_f32 v9, v9, 0, v204
	v_fmac_f32_e32 v2, v180, v6
	v_fmac_f32_e32 v3, v181, v7
	v_med3_f32 v10, v10, 0, v204
	v_med3_f32 v11, v11, 0, v204
	v_fmac_f32_e32 v2, v40, v8
	v_fmac_f32_e32 v3, v41, v9
	v_med3_f32 v12, v12, 0, v204
	v_med3_f32 v13, v13, 0, v204
	v_fmac_f32_e32 v2, v182, v10
	v_fmac_f32_e32 v3, v183, v11
	v_med3_f32 v14, v14, 0, v204
	v_med3_f32 v15, v15, 0, v204
	v_fmac_f32_e32 v2, v34, v12
	v_fmac_f32_e32 v3, v35, v13
	v_med3_f32 v16, v16, 0, v204
	v_med3_f32 v17, v17, 0, v204
	v_fmac_f32_e32 v2, v184, v14
	v_fmac_f32_e32 v3, v185, v15
	v_fma_f32 v4, v36, v16, v2
	v_fma_f32 v5, v37, v17, v3
	v_ashrrev_i32_e32 v2, 31, v4
	v_ashrrev_i32_e32 v6, 31, v5
	v_or_b32_e32 v2, 0x80000000, v2
	v_or_b32_e32 v6, 0x80000000, v6
	v_xor_b32_e32 v3, v4, v2
	v_xor_b32_e32 v2, v5, v6
	v_cmp_gt_u32_e64 s[4:5], v3, v0
	v_cmp_gt_u32_e64 s[6:7], v2, v94
	s_and_b64 s[10:11], s[0:1], s[4:5]
	s_and_b64 s[4:5], s[2:3], s[6:7]
	s_or_b64 s[6:7], s[10:11], s[4:5]
	s_cbranch_scc0 .LBB0_517
	s_and_b64 s[2:3], s[10:11], exec
	s_and_b64 s[0:1], s[4:5], exec
	s_and_saveexec_b64 s[6:7], s[10:11]
	s_cbranch_execz .LBB0_514
	v_mov_b32_e32 v4, s3
	v_mov_b32_e32 v5, s2
	v_cndmask_b32_e32 v4, v4, v5, vcc
	v_and_b32_e32 v4, v4, v218
	v_bcnt_u32_b32 v4, v4, 0
	v_cndmask_b32_e32 v5, v187, v173, vcc
	v_add3_u32 v4, v5, v214, v4
	v_lshl_add_u32 v5, v4, 2, v190
	ds_write_b32 v5, v3
	v_lshlrev_b32_e32 v3, 1, v4
	v_sub_u32_e32 v3, v5, v3
	ds_write_b16 v3, v62 offset:10240

; DI f32x16 mfma32(bf16x8 a, bf16x8 b, f32x16 c) { return __builtin_amdgcn_mfma_f32_32x32x16_bf16(a, b, c, 0, 0, 0); }
; DI u32 mono_key(float f) { u32 u = __float_as_uint(f); return (u & 0x80000000u) ? ~u : (u | 0x80000000u); }
; DI void dsa_item(const Params& p, int l, int tile32, int b, char* smem) {
;     ...
;       for (int t = 0; t < 4; ++t) {
;         const int key = (g * 4 + t) * 32 + c31;
;         f32x16 acc;
; #pragma unroll
;         for (int j = 0; j < 16; ++j) acc[j] = 0.f;
; #pragma unroll
;         for (int s = 0; s < 4; ++s) acc = mfma32(qa[s], kc[t][s], acc);
;         f32x2 ss2 = f32x2{0.f, 0.f};
; #pragma unroll
;         for (int hq = 0; hq < 8; ++hq) {
;           const f32x2 rr = f32x2{__builtin_amdgcn_fmed3f(acc[2 * hq], 0.f, 3.0e38f), __builtin_amdgcn_fmed3f(acc[2 * hq + 1], 0.f, 3.0e38f)};
;           ss2 = __builtin_elementwise_fma(wq2[hq], rr, ss2);
;         }
;         const float s0 = ss2.x, s1 = ss2.y;
;         const u32 k0 = mono_key(s0), k1 = mono_key(s1);
;         const bool c0 = (key <= qpos0) && (k0 > tauA), c1 = (key <= qpos0 + 1) && (k1 > tauB);
;         const u64 m0 = __ballot(c0), m1 = __ballot(c1);
;         if (m0 | m1) {
;           const u32 h0 = hh ? (u32)(m0 >> 32) : (u32)m0, h1 = hh ? (u32)(m1 >> 32) : (u32)m1;
;           const int pA = (hh ? cnt2 : cnt0) + __popc(h0 & lmask), pB = (hh ? cnt3 : cnt1) + __popc(h1 & lmask);
;           if (c0) { ckey[(2 * hh) * DCAP + pA] = k0; cidx[(2 * hh) * DCAP + pA] = (u16)key; }
;           if (c1) { ckey[(2 * hh + 1) * DCAP + pB] = k1; cidx[(2 * hh + 1) * DCAP + pB] = (u16)key; }
;           cnt0 += __popc((u32)m0); cnt2 += __popc((u32)(m0 >> 32));
;           cnt1 += __popc((u32)m1); cnt3 += __popc((u32)(m1 >> 32));
;         }
.LBB0_517:
	v_mfma_f32_32x32x16_bf16 v[2:17], v[18:21], v[54:57], 0
	v_mfma_f32_32x32x16_bf16 v[2:17], v[22:25], v[50:53], v[2:17]
	v_mfma_f32_32x32x16_bf16 v[2:17], v[26:29], v[46:49], v[2:17]
	v_mfma_f32_32x32x16_bf16 v[2:17], v[30:33], v[42:45], v[2:17]
	v_or_b32_e32 v46, 0x60, v95
	v_cmp_le_i32_e64 s[0:1], v46, v217
	v_cmp_le_i32_e64 s[2:3], v46, v219
	s_nop 8
	v_med3_f32 v2, v2, 0, v204
	v_med3_f32 v3, v3, 0, v204
	v_med3_f32 v4, v4, 0, v204
	v_med3_f32 v5, v5, 0, v204
	v_fma_f32 v2, v178, v2, 0
	v_fma_f32 v3, v179, v3, 0
	v_med3_f32 v6, v6, 0, v204
	v_med3_f32 v7, v7, 0, v204
	v_fmac_f32_e32 v2, v38, v4
	v_fmac_f32_e32 v3, v39, v5
	v_med3_f32 v8, v8, 0, v204
	v_med3_f32 v9, v9, 0, v204
	v_fmac_f32_e32 v2, v180, v6
	v_fmac_f32_e32 v3, v181, v7
	v_med3_f32 v10, v10, 0, v204
	v_med3_f32 v11, v11, 0, v204
	v_fmac_f32_e32 v2, v40, v8
	v_fmac_f32_e32 v3, v41, v9
	v_med3_f32 v12, v12, 0, v204
	v_med3_f32 v13, v13, 0, v204
	v_fmac_f32_e32 v2, v182, v10
	v_fmac_f32_e32 v3, v183, v11
	v_med3_f32 v14, v14, 0, v204
	v_med3_f32 v15, v15, 0, v204
	v_fmac_f32_e32 v2, v34, v12
	v_fmac_f32_e32 v3, v35, v13
	v_med3_f32 v16, v16, 0, v204
	v_med3_f32 v17, v17, 0, v204
	v_fmac_f32_e32 v2, v184, v14
	v_fmac_f32_e32 v3, v185, v15
	v_fma_f32 v4, v36, v16, v2
	v_fma_f32 v5, v37, v17, v3
	v_ashrrev_i32_e32 v2, 31, v4
	v_ashrrev_i32_e32 v6, 31, v5
	v_or_b32_e32 v2, 0x80000000, v2
	v_or_b32_e32 v6, 0x80000000, v6
	v_xor_b32_e32 v3, v4, v2
	v_xor_b32_e32 v2, v5, v6
	v_cmp_gt_u32_e64 s[4:5], v3, v0
	v_cmp_gt_u32_e64 s[6:7], v2, v94
	s_and_b64 s[10:11], s[0:1], s[4:5]
	s_and_b64 s[4:5], s[2:3], s[6:7]
	s_or_b64 s[6:7], s[10:11], s[4:5]
	s_cbranch_scc0 .LBB0_374
	s_and_b64 s[2:3], s[10:11], exec
	s_and_b64 s[0:1], s[4:5], exec
	s_and_saveexec_b64 s[6:7], s[10:11]
	s_cbranch_execz .LBB0_520
	v_mov_b32_e32 v0, s3
	v_mov_b32_e32 v4, s2
	v_cndmask_b32_e32 v0, v0, v4, vcc
	v_and_b32_e32 v0, v0, v218
	v_bcnt_u32_b32 v0, v0, 0
	v_cndmask_b32_e32 v4, v187, v173, vcc
	v_add3_u32 v0, v4, v214, v0
	v_lshl_add_u32 v4, v0, 2, v190
	v_lshlrev_b32_e32 v0, 1, v0
	v_sub_u32_e32 v0, v4, v0
	ds_write_b32 v4, v3
	ds_write_b16 v0, v46 offset:10240
